# phase 2: waves 4..7 run the GDN conv part first and the low-rank token-shift part last, so the two wave halves of a CU are out of phase (memory and ALU periods overlap)
# speedup vs baseline: 1.0089x; 1.0089x over previous
.LBB0_259:
	s_or_b64 exec, exec, s[0:1]
	s_add_u32 s26, s34, 0xb120000
	s_waitcnt lgkmcnt(0)
	v_mov_b32_e32 v1, v180
	s_addc_u32 s27, s35, 0
	s_barrier
	s_mov_b32 s0, 0
	v_writelane_b32 v242, s0, 57
	v_readfirstlane_b32 s0, v180
	s_nop 1
	s_cmpk_ge_u32 s0, 0x100
	s_cbranch_scc1 .Lp2_b
.Lp2_a:
	s_add_u32 s8, s34, 0x16220000
	v_add_u32_e32 v42, s88, v1
	s_mov_b32 s0, 0x40000
	s_addc_u32 s9, s35, 0
	v_cmp_gt_i32_e32 vcc, s0, v42
	s_and_saveexec_b64 s[4:5], vcc
	s_cbranch_execz .LBB0_360
	v_and_b32_e32 v8, 0x7f, v1
	v_lshlrev_b32_e32 v2, 2, v8
	v_mov_b32_e32 v3, 0
	v_lshl_add_u64 v[4:5], s[26:27], 0, v[2:3]
	v_lshl_add_u64 v[6:7], s[42:43], 0, v[2:3]
	s_mov_b64 s[0:1], 0x1800
	v_lshlrev_b32_e32 v2, 1, v8
	s_lshl_b32 s3, s18, 9
	v_cmp_gt_u32_e32 vcc, 64, v8
	v_lshl_add_u64 v[6:7], v[6:7], 0, s[0:1]
	v_lshl_add_u64 v[8:9], s[8:9], 0, v[2:3]
	s_mov_b64 s[6:7], 0
	s_movk_i32 s14, 0x220
	s_mov_b32 s15, 0x3f200000
	s_mov_b32 s16, 0x3fb8aa3b
	s_mov_b32 s17, 0xc2ce8ed0
	s_mov_b32 s22, 0x42b17218
	v_mov_b32_e32 v2, 0x3ca908c9
	s_brev_b32 s23, -2
	s_movk_i32 s24, 0x7fff
	s_mov_b32 s25, 0x3ffff
	v_mov_b32_e32 v43, 0x7f800000
	s_branch .LBB0_263

.LBB0_360:
	s_or_b64 exec, exec, s[4:5]
	v_readlane_b32 s0, v242, 57
	s_nop 1
	s_cmp_eq_u32 s0, 1
	s_cbranch_scc1 .Lp2_end
.Lp2_b:
	s_add_u32 s24, s34, 0xe220000
	s_addc_u32 s25, s35, 0
	v_ashrrev_i32_e32 v2, 6, v1
	s_add_u32 s22, s34, 0x19220000
	v_add_u32_e32 v94, s95, v2
	s_movk_i32 s0, 0x1800
	s_addc_u32 s23, s35, 0
	v_cmp_gt_i32_e32 vcc, s0, v94
	s_and_saveexec_b64 s[4:5], vcc
	s_cbranch_execz .LBB0_397
	v_lshlrev_b32_e32 v2, 9, v2
	v_lshlrev_b32_e32 v1, 3, v1
	v_lshl_add_u32 v2, s2, 12, v2
	s_movk_i32 s0, 0x1f8
	v_and_or_b32 v96, v1, s0, v2
	s_lshl_b32 s16, s33, 9
	s_mov_b64 s[6:7], 0
	s_mov_b32 s17, 0x55555556
	s_movk_i32 s46, 0xfa00
	s_mov_b64 s[10:11], 0x1800
	s_mov_b64 s[12:13], 0x3000
	s_mov_b64 s[14:15], 0x4800
	s_movk_i32 s47, 0xc00
	s_mov_b32 s50, 0x800000
	s_movk_i32 s51, 0x17ff
	s_branch .LBB0_363

.LBB0_397:
	s_or_b64 exec, exec, s[4:5]
	v_readfirstlane_b32 s0, v180
	s_nop 1
	s_cmpk_ge_u32 s0, 0x100
	s_cbranch_scc0 .Lp2_end
	s_mov_b32 s0, 1
	v_writelane_b32 v242, s0, 57
	v_mov_b32_e32 v1, v180
	s_branch .Lp2_a
.Lp2_end:
	s_add_u32 s24, s34, 0xe220000
	s_addc_u32 s25, s35, 0
	s_add_u32 s22, s34, 0x19220000
	s_addc_u32 s23, s35, 0
	s_waitcnt vmcnt(0)
	s_barrier
	s_mov_b64 s[0:1], exec
	v_readlane_b32 s4, v242, 6
	v_readlane_b32 s5, v242, 7
	s_and_b64 s[4:5], s[0:1], s[4:5]
	s_mov_b64 exec, s[4:5]
	s_cbranch_execz .LBB0_449
	s_add_i32 s3, 0, 0x27ff0
	v_mov_b32_e32 v1, s3
	s_waitcnt vmcnt(0) expcnt(0) lgkmcnt(0)
	ds_read_b32 v3, v1
	s_add_i32 s3, 0, 0x27ff4
	v_mov_b32_e32 v1, s3
	ds_read_b32 v1, v1
	s_waitcnt lgkmcnt(1)
	v_cmp_ne_u32_e32 vcc, 0, v3
	s_cbranch_vccnz .LBB0_413
	s_add_u32 s4, s34, 0x1f220200
	s_addc_u32 s5, s35, 0
	s_add_u32 s6, s34, 0x1f220400
	s_addc_u32 s7, s35, 0
	s_add_u32 s10, s34, 0x1f220500
	s_addc_u32 s11, s35, 0
	s_add_u32 s12, s34, 0x1f220600
	s_addc_u32 s13, s35, 0
	s_add_u32 s14, s34, 0x1f220700
	s_addc_u32 s15, s35, 0
	s_add_u32 s40, s34, 0x1f220800
	s_addc_u32 s41, s35, 0
	s_add_u32 s46, s34, 0x1f220900
	s_addc_u32 s47, s35, 0
	s_add_u32 s50, s34, 0x1f220a00
	s_addc_u32 s51, s35, 0
	s_add_u32 s62, s34, 0x1f220b00
	s_addc_u32 s63, s35, 0
	s_add_u32 s72, s34, 0x1f220c00
	s_addc_u32 s73, s35, 0
	s_add_u32 s74, s34, 0x1f220d00
	s_addc_u32 s75, s35, 0
	s_add_u32 s76, s34, 0x1f220e00
	s_addc_u32 s77, s35, 0
	s_add_u32 s78, s34, 0x1f220f00
	s_addc_u32 s79, s35, 0
	s_add_u32 s80, s34, 0x1f221000
	s_addc_u32 s81, s35, 0
	s_add_u32 s82, s34, 0x1f221100
	s_addc_u32 s83, s35, 0
	s_add_u32 s84, s34, 0x1f221200
	v_readlane_b32 s3, v242, 0
	s_addc_u32 s85, s35, 0
	s_mul_i32 s3, s19, s3
	s_add_u32 s86, s34, 0x1f221300
	s_mul_i32 s3, s3, s18
	s_addc_u32 s87, s35, 0
	s_mov_b32 s16, 1
	v_mov_b32_e32 v17, 0
	s_branch .LBB0_401
